# diff attention loops: packed f32 adds of the row sums split into plain v_add_f32 pairs
# speedup vs baseline: 1.0255x; 1.0012x over previous
.LBB0_171:
	v_add_f32_e32 v119, 0, v119
	v_add_f32_e32 v120, 0, v120
	v_add_f32_e32 v119, v121, v119
	v_add_f32_e32 v120, v122, v120
	v_add_f32_e32 v119, v123, v119
	v_add_f32_e32 v120, v125, v120
	v_add_f32_e32 v119, v126, v119
	v_add_f32_e32 v120, v127, v120
	v_add_f32_e32 v119, v130, v119
	v_exp_f32_e32 v125, v80
	v_exp_f32_e32 v130, v64
	v_add_f32_e32 v120, v131, v120
	v_add_f32_e32 v119, v132, v119
	v_exp_f32_e32 v131, v81
	v_exp_f32_e32 v132, v65
	v_add_f32_e32 v120, v133, v120
	v_add_f32_e32 v119, v134, v119
	v_exp_f32_e32 v133, v82
	v_exp_f32_e32 v134, v66
	v_add_f32_e32 v120, v135, v120
	v_add_f32_e32 v119, v140, v119
	v_exp_f32_e32 v135, v83
	v_exp_f32_e32 v140, v67
	v_add_f32_e32 v120, v141, v120
	v_add_f32_e32 v64, 0, v125
	v_add_f32_e32 v80, 0, v130
	v_add_f32_e32 v119, v142, v119
	v_add_f32_e32 v120, v143, v120
	v_add_f32_e32 v64, v131, v64
	v_add_f32_e32 v65, v132, v80
	v_add_f32_e32 v119, v144, v119
	v_add_f32_e32 v120, v145, v120
	v_add_f32_e32 v64, v133, v64
	v_add_f32_e32 v66, v134, v65
	v_add_f32_e32 v119, v146, v119
	v_add_f32_e32 v120, v147, v120
	v_add_f32_e32 v65, v135, v64
	v_add_f32_e32 v64, v140, v66
	v_exp_f32_e32 v67, v84
	v_exp_f32_e32 v66, v68
	v_add_f32_e32 v119, v148, v119
	v_add_f32_e32 v120, v149, v120
	v_exp_f32_e32 v81, v85
	v_exp_f32_e32 v80, v69
	v_add_f32_e32 v119, v150, v119
	v_add_f32_e32 v120, v151, v120
	v_exp_f32_e32 v83, v86
	v_exp_f32_e32 v82, v70
	v_add_f32_e32 v119, v152, v119
	v_add_f32_e32 v120, v153, v120
	v_exp_f32_e32 v85, v87
	v_exp_f32_e32 v84, v71
	v_add_f32_e32 v119, v154, v119
	v_add_f32_e32 v120, v155, v120
	v_exp_f32_e32 v87, v88
	v_exp_f32_e32 v86, v72
	v_add_f32_e32 v64, v66, v64
	v_add_f32_e32 v65, v67, v65
	v_add_f32_e32 v119, v156, v119
	v_add_f32_e32 v120, v157, v120
	v_exp_f32_e32 v89, v89
	v_exp_f32_e32 v88, v73
	v_add_f32_e32 v64, v80, v64
	v_add_f32_e32 v65, v81, v65
	v_add_f32_e32 v119, v120, v119
	v_exp_f32_e32 v121, v90
	v_exp_f32_e32 v120, v74
	v_add_f32_e32 v64, v82, v64
	v_add_f32_e32 v65, v83, v65
	v_exp_f32_e32 v91, v91
	v_exp_f32_e32 v90, v75
	v_add_f32_e32 v64, v84, v64
	v_add_f32_e32 v65, v85, v65
	v_exp_f32_e32 v123, v92
	v_exp_f32_e32 v122, v76
	v_add_f32_e32 v64, v86, v64
	v_add_f32_e32 v65, v87, v65
	v_exp_f32_e32 v93, v93
	v_exp_f32_e32 v92, v77
	v_add_f32_e32 v64, v88, v64
	v_add_f32_e32 v65, v89, v65
	v_exp_f32_e32 v127, v94
	v_exp_f32_e32 v126, v78
	v_add_f32_e32 v64, v120, v64
	v_add_f32_e32 v65, v121, v65
	v_exp_f32_e32 v95, v95
	v_exp_f32_e32 v94, v79
	v_add_f32_e32 v64, v90, v64
	v_add_f32_e32 v65, v91, v65
	v_cvt_pk_bf16_f32 v71, v82, v84
	v_add_f32_e32 v64, v122, v64
	v_add_f32_e32 v65, v123, v65
	v_cvt_pk_bf16_f32 v78, v67, v81
	v_add_f32_e32 v64, v92, v64
	v_add_f32_e32 v65, v93, v65
	v_cvt_pk_bf16_f32 v79, v83, v85
	v_add_f32_e32 v64, v126, v64
	v_add_f32_e32 v65, v127, v65
	v_cvt_pk_bf16_f32 v70, v66, v80
	v_add_f32_e32 v64, v94, v64
	v_add_f32_e32 v65, v95, v65
	v_cvt_pk_bf16_f32 v72, v87, v89
	v_add_f32_e32 v141, v64, v65
	v_cvt_pk_bf16_f32 v64, v86, v88
	v_add_u32_e32 v88, s8, v112
	v_add_u32_e32 v84, v88, v114
	ds_read_b128 v[80:83], v84 offset:4096
	ds_read_b128 v[84:87], v84 offset:8192
	v_cvt_pk_bf16_f32 v76, v125, v131
	v_cvt_pk_bf16_f32 v77, v133, v135
	v_cvt_pk_bf16_f32 v73, v121, v91
	v_cvt_pk_bf16_f32 v74, v123, v93
	s_waitcnt lgkmcnt(0)
	v_mfma_f32_32x32x16_bf16 v[0:15], v[80:83], v[76:79], v[0:15]
	v_add_u32_e32 v80, v88, v124
	v_cvt_pk_bf16_f32 v75, v127, v95
	v_cvt_pk_bf16_f32 v68, v130, v132
	v_cvt_pk_bf16_f32 v69, v134, v140
	v_cvt_pk_bf16_f32 v65, v120, v90
	v_cvt_pk_bf16_f32 v66, v122, v92
	v_cvt_pk_bf16_f32 v67, v126, v94
	v_mfma_f32_32x32x16_bf16 v[16:31], v[84:87], v[76:79], v[16:31]
	ds_read_b128 v[76:79], v80 offset:4096
	ds_read_b128 v[80:83], v80 offset:8192
	v_add_f32_e32 v119, v175, v119
	s_add_i32 s50, s50, 2
	v_add_f32_e32 v175, v141, v119
	s_cmp_lt_u32 s50, s11
	s_waitcnt lgkmcnt(0)
	v_mfma_f32_32x32x16_bf16 v[0:15], v[76:79], v[72:75], v[0:15]
	v_add_u32_e32 v76, v88, v128
	v_mfma_f32_32x32x16_bf16 v[16:31], v[80:83], v[72:75], v[16:31]
	ds_read_b128 v[72:75], v76 offset:4096
	ds_read_b128 v[76:79], v76 offset:8192
	s_waitcnt lgkmcnt(0)
	v_mfma_f32_32x32x16_bf16 v[0:15], v[72:75], v[68:71], v[0:15]
	v_add_u32_e32 v72, v88, v129
	v_mfma_f32_32x32x16_bf16 v[16:31], v[76:79], v[68:71], v[16:31]
	ds_read_b128 v[68:71], v72 offset:4096
	ds_read_b128 v[72:75], v72 offset:8192
	s_waitcnt vmcnt(0)
	s_waitcnt vmcnt(0) lgkmcnt(0)
	s_barrier
	v_mfma_f32_32x32x16_bf16 v[0:15], v[68:71], v[64:67], v[0:15]
	v_mfma_f32_32x32x16_bf16 v[16:31], v[72:75], v[64:67], v[16:31]
	s_cbranch_scc0 .LBB0_174
	s_mov_b32 s2, s12
	s_mov_b32 s12, s51
	s_branch .LBB0_160

.LBB0_202:
	v_add_f32_e32 v150, 0, v150
	v_add_f32_e32 v151, 0, v151
	v_add_f32_e32 v150, v152, v150
	v_add_f32_e32 v151, v153, v151
	v_add_f32_e32 v150, v154, v150
	v_add_f32_e32 v151, v155, v151
	v_add_f32_e32 v150, v156, v150
	v_add_f32_e32 v151, v157, v151
	v_add_f32_e32 v150, v158, v150
	v_add_f32_e32 v151, v159, v151
	v_add_f32_e32 v150, v160, v150
	v_add_f32_e32 v151, v161, v151
	v_add_f32_e32 v150, v162, v150
	v_add_f32_e32 v151, v163, v151
	v_add_f32_e32 v150, v164, v150
	v_add_f32_e32 v151, v165, v151
	v_add_f32_e32 v150, v166, v150
	v_add_f32_e32 v151, v167, v151
	v_add_f32_e32 v150, v168, v150
	v_add_f32_e32 v151, v169, v151
	v_add_f32_e32 v150, v175, v150
	v_add_f32_e32 v151, v176, v151
	v_add_f32_e32 v150, v177, v150
	v_add_f32_e32 v151, v185, v151
	v_add_f32_e32 v150, v186, v150
	v_add_f32_e32 v151, v187, v151
	v_add_f32_e32 v150, v188, v150
	v_add_f32_e32 v151, v189, v151
	v_add_f32_e32 v150, v190, v150
	v_add_f32_e32 v151, v191, v151
	v_add_f32_e32 v150, v192, v150
	v_add_f32_e32 v151, v206, v151
	v_add_f32_e32 v150, v151, v150
	v_exp_f32_e32 v151, v112
	v_exp_f32_e32 v160, v96
	v_exp_f32_e32 v113, v113
	v_exp_f32_e32 v161, v97
	v_exp_f32_e32 v162, v114
	v_exp_f32_e32 v163, v98
	v_exp_f32_e32 v164, v115
	v_exp_f32_e32 v165, v99
	v_add_f32_e32 v96, 0, v151
	v_add_f32_e32 v112, 0, v160
	v_add_f32_e32 v96, v113, v96
	v_add_f32_e32 v97, v161, v112
	v_add_f32_e32 v96, v162, v96
	v_add_f32_e32 v98, v163, v97
	v_add_f32_e32 v97, v164, v96
	v_add_f32_e32 v96, v165, v98
	v_exp_f32_e32 v99, v116
	v_exp_f32_e32 v98, v100
	v_exp_f32_e32 v115, v117
	v_exp_f32_e32 v114, v101
	v_exp_f32_e32 v117, v118
	v_exp_f32_e32 v116, v102
	v_exp_f32_e32 v119, v119
	v_exp_f32_e32 v118, v103
	v_exp_f32_e32 v153, v120
	v_exp_f32_e32 v152, v104
	v_add_f32_e32 v96, v98, v96
	v_add_f32_e32 v97, v99, v97
	v_exp_f32_e32 v121, v121
	v_exp_f32_e32 v120, v105
	v_add_f32_e32 v96, v114, v96
	v_add_f32_e32 v97, v115, v97
	v_exp_f32_e32 v155, v122
	v_exp_f32_e32 v154, v106
	v_add_f32_e32 v96, v116, v96
	v_add_f32_e32 v97, v117, v97
	v_exp_f32_e32 v123, v123
	v_exp_f32_e32 v122, v107
	v_add_f32_e32 v96, v118, v96
	v_add_f32_e32 v97, v119, v97
	v_exp_f32_e32 v157, v124
	v_exp_f32_e32 v156, v108
	v_add_f32_e32 v96, v152, v96
	v_add_f32_e32 v97, v153, v97
	v_exp_f32_e32 v125, v125
	v_exp_f32_e32 v124, v109
	v_add_f32_e32 v96, v120, v96
	v_add_f32_e32 v97, v121, v97
	v_exp_f32_e32 v159, v126
	v_exp_f32_e32 v158, v110
	v_add_f32_e32 v96, v154, v96
	v_add_f32_e32 v97, v155, v97
	v_exp_f32_e32 v127, v127
	v_exp_f32_e32 v126, v111
	v_add_f32_e32 v96, v122, v96
	v_add_f32_e32 v97, v123, v97
	v_cvt_pk_bf16_f32 v108, v151, v113
	v_add_f32_e32 v96, v156, v96
	v_add_f32_e32 v97, v157, v97
	v_add_u32_e32 v113, s42, v179
	v_add_f32_e32 v96, v124, v96
	v_add_f32_e32 v97, v125, v97
	v_cvt_pk_bf16_f32 v103, v116, v118
	v_add_f32_e32 v96, v158, v96
	v_add_f32_e32 v97, v159, v97
	v_add_u32_e32 v118, v113, v180
	v_add_f32_e32 v96, v126, v96
	v_add_f32_e32 v97, v127, v97
	v_cvt_pk_bf16_f32 v110, v99, v115
	v_cvt_pk_bf16_f32 v111, v117, v119
	v_cvt_pk_bf16_f32 v102, v98, v114
	ds_read_b128 v[114:117], v118 offset:4096
	v_add_f32_e32 v112, v96, v97
	v_cvt_pk_bf16_f32 v104, v153, v121
	v_cvt_pk_bf16_f32 v96, v152, v120
	ds_read_b128 v[118:121], v118 offset:8192
	v_cvt_pk_bf16_f32 v109, v162, v164
	v_cvt_pk_bf16_f32 v105, v155, v123
	v_cvt_pk_bf16_f32 v106, v157, v125
	s_waitcnt lgkmcnt(0)
	v_mfma_f32_32x32x16_bf16 v[32:47], v[114:117], v[108:111], v[32:47]
	v_add_u32_e32 v114, v113, v181
	v_cvt_pk_bf16_f32 v107, v159, v127
	v_cvt_pk_bf16_f32 v100, v160, v161
	v_cvt_pk_bf16_f32 v101, v163, v165
	v_cvt_pk_bf16_f32 v97, v154, v122
	v_cvt_pk_bf16_f32 v98, v156, v124
	v_cvt_pk_bf16_f32 v99, v158, v126
	v_mfma_f32_32x32x16_bf16 v[48:63], v[118:121], v[108:111], v[48:63]
	ds_read_b128 v[108:111], v114 offset:4096
	ds_read_b128 v[114:117], v114 offset:8192
	v_add_f32_e32 v150, v184, v150
	s_add_i32 s17, s17, 2
	v_add_f32_e32 v184, v112, v150
	s_cmp_lt_u32 s17, s11
	s_waitcnt lgkmcnt(0)
	v_mfma_f32_32x32x16_bf16 v[32:47], v[108:111], v[104:107], v[32:47]
	v_add_u32_e32 v108, v113, v182
	v_mfma_f32_32x32x16_bf16 v[48:63], v[114:117], v[104:107], v[48:63]
	ds_read_b128 v[104:107], v108 offset:4096
	ds_read_b128 v[108:111], v108 offset:8192
	s_waitcnt lgkmcnt(0)
	v_mfma_f32_32x32x16_bf16 v[32:47], v[104:107], v[100:103], v[32:47]
	v_add_u32_e32 v104, v113, v183
	v_mfma_f32_32x32x16_bf16 v[48:63], v[108:111], v[100:103], v[48:63]
	ds_read_b128 v[100:103], v104 offset:4096
	ds_read_b128 v[104:107], v104 offset:8192
	s_waitcnt vmcnt(0)
	s_waitcnt vmcnt(0) lgkmcnt(0)
	s_barrier
	v_mfma_f32_32x32x16_bf16 v[32:47], v[100:103], v[96:99], v[32:47]
	v_mfma_f32_32x32x16_bf16 v[48:63], v[104:107], v[96:99], v[48:63]
	s_cbranch_scc0 .LBB0_205
	s_mov_b32 s2, s12
	s_mov_b32 s12, s10
	s_branch .LBB0_191
